# EpiGate epilogue: all 16/32 gate+merged loads issued up front with counted vmcnt instead of one round trip per 16B
# speedup vs baseline: 1.0067x; 1.0067x over previous
.LBB0_1338:
	v_and_b32_e32 v138, 15, v206
	v_lshrrev_b32_e32 v140, 1, v206
	v_and_b32_e32 v140, 24, v140
	s_lshl_b32 s8, s48, 8
	s_add_i32 s8, s8, s43
	s_lshl_b32 s9, s47, 8
	s_add_i32 s9, s9, s44
	v_add_u32_e32 v138, s8, v138
	v_add_u32_e32 v140, s9, v140
	v_lshlrev_b32_e32 v138, 11, v138
	v_lshl_add_u32 v138, v140, 1, v138
	v_add_u32_e32 v139, 0x8000, v138
	v_add_u32_e32 v142, 0x10000, v138
	v_add_u32_e32 v144, 0x18000, v138
	v_add_u32_e32 v145, 0x40000, v138
	v_add_u32_e32 v146, 0x48000, v138
	v_add_u32_e32 v147, 0x50000, v138
	v_add_u32_e32 v219, 0x58000, v138
	s_and_b64 vcc, exec, s[2:3]
	s_cbranch_vccnz .Lgate_second
	global_load_dwordx4 v[160:163], v138, s[10:11]
	global_load_dwordx4 v[164:167], v138, s[10:11] offset:256
	global_load_dwordx4 v[168:171], v139, s[10:11]
	global_load_dwordx4 v[172:175], v139, s[10:11] offset:256
	global_load_dwordx4 v[176:179], v142, s[10:11]
	global_load_dwordx4 v[180:183], v142, s[10:11] offset:256
	global_load_dwordx4 v[184:187], v144, s[10:11]
	global_load_dwordx4 v[188:191], v144, s[10:11] offset:256
	global_load_dwordx4 v[192:195], v145, s[10:11]
	global_load_dwordx4 v[196:199], v145, s[10:11] offset:256
	global_load_dwordx4 v[200:203], v146, s[10:11]
	global_load_dwordx4 v[212:215], v146, s[10:11] offset:256
	global_load_dwordx4 v[220:223], v147, s[10:11]
	global_load_dwordx4 v[224:227], v147, s[10:11] offset:256
	global_load_dwordx4 v[228:231], v219, s[10:11]
	global_load_dwordx4 v[232:235], v219, s[10:11] offset:256
	s_waitcnt vmcnt(15)
	v_lshlrev_b32_e32 v140, 16, v160
	v_and_b32_e32 v141, 0xffff0000, v160
	v_pk_mul_f32 v[124:125], v[124:125], v[140:141]
	v_lshlrev_b32_e32 v150, 16, v161
	v_and_b32_e32 v151, 0xffff0000, v161
	v_pk_mul_f32 v[126:127], v[126:127], v[150:151]
	v_lshlrev_b32_e32 v156, 16, v162
	v_and_b32_e32 v157, 0xffff0000, v162
	v_pk_mul_f32 v[120:121], v[120:121], v[156:157]
	v_lshlrev_b32_e32 v204, 16, v163
	v_and_b32_e32 v205, 0xffff0000, v163
	v_pk_mul_f32 v[122:123], v[122:123], v[204:205]
	v_cvt_pk_bf16_f32 v124, v124, v125
	v_cvt_pk_bf16_f32 v125, v126, v127
	v_cvt_pk_bf16_f32 v126, v120, v121
	v_cvt_pk_bf16_f32 v127, v122, v123
	global_store_dwordx4 v138, v[124:127], s[0:1]
	s_waitcnt vmcnt(15)
	v_lshlrev_b32_e32 v140, 16, v164
	v_and_b32_e32 v141, 0xffff0000, v164
	v_pk_mul_f32 v[116:117], v[116:117], v[140:141]
	v_lshlrev_b32_e32 v150, 16, v165
	v_and_b32_e32 v151, 0xffff0000, v165
	v_pk_mul_f32 v[118:119], v[118:119], v[150:151]
	v_lshlrev_b32_e32 v156, 16, v166
	v_and_b32_e32 v157, 0xffff0000, v166
	v_pk_mul_f32 v[112:113], v[112:113], v[156:157]
	v_lshlrev_b32_e32 v204, 16, v167
	v_and_b32_e32 v205, 0xffff0000, v167
	v_pk_mul_f32 v[114:115], v[114:115], v[204:205]
	v_cvt_pk_bf16_f32 v116, v116, v117
	v_cvt_pk_bf16_f32 v117, v118, v119
	v_cvt_pk_bf16_f32 v118, v112, v113
	v_cvt_pk_bf16_f32 v119, v114, v115
	global_store_dwordx4 v138, v[116:119], s[0:1] offset:256
	s_waitcnt vmcnt(15)
	v_lshlrev_b32_e32 v140, 16, v168
	v_and_b32_e32 v141, 0xffff0000, v168
	v_pk_mul_f32 v[108:109], v[108:109], v[140:141]
	v_lshlrev_b32_e32 v150, 16, v169
	v_and_b32_e32 v151, 0xffff0000, v169
	v_pk_mul_f32 v[110:111], v[110:111], v[150:151]
	v_lshlrev_b32_e32 v156, 16, v170
	v_and_b32_e32 v157, 0xffff0000, v170
	v_pk_mul_f32 v[104:105], v[104:105], v[156:157]
	v_lshlrev_b32_e32 v204, 16, v171
	v_and_b32_e32 v205, 0xffff0000, v171
	v_pk_mul_f32 v[106:107], v[106:107], v[204:205]
	v_cvt_pk_bf16_f32 v108, v108, v109
	v_cvt_pk_bf16_f32 v109, v110, v111
	v_cvt_pk_bf16_f32 v110, v104, v105
	v_cvt_pk_bf16_f32 v111, v106, v107
	global_store_dwordx4 v139, v[108:111], s[0:1]
	s_waitcnt vmcnt(15)
	v_lshlrev_b32_e32 v140, 16, v172
	v_and_b32_e32 v141, 0xffff0000, v172
	v_pk_mul_f32 v[100:101], v[100:101], v[140:141]
	v_lshlrev_b32_e32 v150, 16, v173
	v_and_b32_e32 v151, 0xffff0000, v173
	v_pk_mul_f32 v[102:103], v[102:103], v[150:151]
	v_lshlrev_b32_e32 v156, 16, v174
	v_and_b32_e32 v157, 0xffff0000, v174
	v_pk_mul_f32 v[96:97], v[96:97], v[156:157]
	v_lshlrev_b32_e32 v204, 16, v175
	v_and_b32_e32 v205, 0xffff0000, v175
	v_pk_mul_f32 v[98:99], v[98:99], v[204:205]
	v_cvt_pk_bf16_f32 v100, v100, v101
	v_cvt_pk_bf16_f32 v101, v102, v103
	v_cvt_pk_bf16_f32 v102, v96, v97
	v_cvt_pk_bf16_f32 v103, v98, v99
	global_store_dwordx4 v139, v[100:103], s[0:1] offset:256
	s_waitcnt vmcnt(15)
	v_lshlrev_b32_e32 v140, 16, v176
	v_and_b32_e32 v141, 0xffff0000, v176
	v_pk_mul_f32 v[92:93], v[92:93], v[140:141]
	v_lshlrev_b32_e32 v150, 16, v177
	v_and_b32_e32 v151, 0xffff0000, v177
	v_pk_mul_f32 v[94:95], v[94:95], v[150:151]
	v_lshlrev_b32_e32 v156, 16, v178
	v_and_b32_e32 v157, 0xffff0000, v178
	v_pk_mul_f32 v[88:89], v[88:89], v[156:157]
	v_lshlrev_b32_e32 v204, 16, v179
	v_and_b32_e32 v205, 0xffff0000, v179
	v_pk_mul_f32 v[90:91], v[90:91], v[204:205]
	v_cvt_pk_bf16_f32 v92, v92, v93
	v_cvt_pk_bf16_f32 v93, v94, v95
	v_cvt_pk_bf16_f32 v94, v88, v89
	v_cvt_pk_bf16_f32 v95, v90, v91
	global_store_dwordx4 v142, v[92:95], s[0:1]
	s_waitcnt vmcnt(15)
	v_lshlrev_b32_e32 v140, 16, v180
	v_and_b32_e32 v141, 0xffff0000, v180
	v_pk_mul_f32 v[84:85], v[84:85], v[140:141]
	v_lshlrev_b32_e32 v150, 16, v181
	v_and_b32_e32 v151, 0xffff0000, v181
	v_pk_mul_f32 v[86:87], v[86:87], v[150:151]
	v_lshlrev_b32_e32 v156, 16, v182
	v_and_b32_e32 v157, 0xffff0000, v182
	v_pk_mul_f32 v[80:81], v[80:81], v[156:157]
	v_lshlrev_b32_e32 v204, 16, v183
	v_and_b32_e32 v205, 0xffff0000, v183
	v_pk_mul_f32 v[82:83], v[82:83], v[204:205]
	v_cvt_pk_bf16_f32 v84, v84, v85
	v_cvt_pk_bf16_f32 v85, v86, v87
	v_cvt_pk_bf16_f32 v86, v80, v81
	v_cvt_pk_bf16_f32 v87, v82, v83
	global_store_dwordx4 v142, v[84:87], s[0:1] offset:256
	s_waitcnt vmcnt(15)
	v_lshlrev_b32_e32 v140, 16, v184
	v_and_b32_e32 v141, 0xffff0000, v184
	v_pk_mul_f32 v[76:77], v[76:77], v[140:141]
	v_lshlrev_b32_e32 v150, 16, v185
	v_and_b32_e32 v151, 0xffff0000, v185
	v_pk_mul_f32 v[78:79], v[78:79], v[150:151]
	v_lshlrev_b32_e32 v156, 16, v186
	v_and_b32_e32 v157, 0xffff0000, v186
	v_pk_mul_f32 v[72:73], v[72:73], v[156:157]
	v_lshlrev_b32_e32 v204, 16, v187
	v_and_b32_e32 v205, 0xffff0000, v187
	v_pk_mul_f32 v[74:75], v[74:75], v[204:205]
	v_cvt_pk_bf16_f32 v76, v76, v77
	v_cvt_pk_bf16_f32 v77, v78, v79
	v_cvt_pk_bf16_f32 v78, v72, v73
	v_cvt_pk_bf16_f32 v79, v74, v75
	global_store_dwordx4 v144, v[76:79], s[0:1]
	s_waitcnt vmcnt(15)
	v_lshlrev_b32_e32 v140, 16, v188
	v_and_b32_e32 v141, 0xffff0000, v188
	v_pk_mul_f32 v[68:69], v[68:69], v[140:141]
	v_lshlrev_b32_e32 v150, 16, v189
	v_and_b32_e32 v151, 0xffff0000, v189
	v_pk_mul_f32 v[70:71], v[70:71], v[150:151]
	v_lshlrev_b32_e32 v156, 16, v190
	v_and_b32_e32 v157, 0xffff0000, v190
	v_pk_mul_f32 v[64:65], v[64:65], v[156:157]
	v_lshlrev_b32_e32 v204, 16, v191
	v_and_b32_e32 v205, 0xffff0000, v191
	v_pk_mul_f32 v[66:67], v[66:67], v[204:205]
	v_cvt_pk_bf16_f32 v68, v68, v69
	v_cvt_pk_bf16_f32 v69, v70, v71
	v_cvt_pk_bf16_f32 v70, v64, v65
	v_cvt_pk_bf16_f32 v71, v66, v67
	global_store_dwordx4 v144, v[68:71], s[0:1] offset:256
	s_waitcnt vmcnt(15)
	v_lshlrev_b32_e32 v140, 16, v192
	v_and_b32_e32 v141, 0xffff0000, v192
	v_pk_mul_f32 v[60:61], v[60:61], v[140:141]
	v_lshlrev_b32_e32 v150, 16, v193
	v_and_b32_e32 v151, 0xffff0000, v193
	v_pk_mul_f32 v[62:63], v[62:63], v[150:151]
	v_lshlrev_b32_e32 v156, 16, v194
	v_and_b32_e32 v157, 0xffff0000, v194
	v_pk_mul_f32 v[56:57], v[56:57], v[156:157]
	v_lshlrev_b32_e32 v204, 16, v195
	v_and_b32_e32 v205, 0xffff0000, v195
	v_pk_mul_f32 v[58:59], v[58:59], v[204:205]
	v_cvt_pk_bf16_f32 v60, v60, v61
	v_cvt_pk_bf16_f32 v61, v62, v63
	v_cvt_pk_bf16_f32 v62, v56, v57
	v_cvt_pk_bf16_f32 v63, v58, v59
	global_store_dwordx4 v145, v[60:63], s[0:1]
	s_waitcnt vmcnt(15)
	v_lshlrev_b32_e32 v140, 16, v196
	v_and_b32_e32 v141, 0xffff0000, v196
	v_pk_mul_f32 v[52:53], v[52:53], v[140:141]
	v_lshlrev_b32_e32 v150, 16, v197
	v_and_b32_e32 v151, 0xffff0000, v197
	v_pk_mul_f32 v[54:55], v[54:55], v[150:151]
	v_lshlrev_b32_e32 v156, 16, v198
	v_and_b32_e32 v157, 0xffff0000, v198
	v_pk_mul_f32 v[48:49], v[48:49], v[156:157]
	v_lshlrev_b32_e32 v204, 16, v199
	v_and_b32_e32 v205, 0xffff0000, v199
	v_pk_mul_f32 v[50:51], v[50:51], v[204:205]
	v_cvt_pk_bf16_f32 v52, v52, v53
	v_cvt_pk_bf16_f32 v53, v54, v55
	v_cvt_pk_bf16_f32 v54, v48, v49
	v_cvt_pk_bf16_f32 v55, v50, v51
	global_store_dwordx4 v145, v[52:55], s[0:1] offset:256
	s_waitcnt vmcnt(15)
	v_lshlrev_b32_e32 v140, 16, v200
	v_and_b32_e32 v141, 0xffff0000, v200
	v_pk_mul_f32 v[44:45], v[44:45], v[140:141]
	v_lshlrev_b32_e32 v150, 16, v201
	v_and_b32_e32 v151, 0xffff0000, v201
	v_pk_mul_f32 v[46:47], v[46:47], v[150:151]
	v_lshlrev_b32_e32 v156, 16, v202
	v_and_b32_e32 v157, 0xffff0000, v202
	v_pk_mul_f32 v[40:41], v[40:41], v[156:157]
	v_lshlrev_b32_e32 v204, 16, v203
	v_and_b32_e32 v205, 0xffff0000, v203
	v_pk_mul_f32 v[42:43], v[42:43], v[204:205]
	v_cvt_pk_bf16_f32 v44, v44, v45
	v_cvt_pk_bf16_f32 v45, v46, v47
	v_cvt_pk_bf16_f32 v46, v40, v41
	v_cvt_pk_bf16_f32 v47, v42, v43
	global_store_dwordx4 v146, v[44:47], s[0:1]
	s_waitcnt vmcnt(15)
	v_lshlrev_b32_e32 v140, 16, v212
	v_and_b32_e32 v141, 0xffff0000, v212
	v_pk_mul_f32 v[36:37], v[36:37], v[140:141]
	v_lshlrev_b32_e32 v150, 16, v213
	v_and_b32_e32 v151, 0xffff0000, v213
	v_pk_mul_f32 v[38:39], v[38:39], v[150:151]
	v_lshlrev_b32_e32 v156, 16, v214
	v_and_b32_e32 v157, 0xffff0000, v214
	v_pk_mul_f32 v[32:33], v[32:33], v[156:157]
	v_lshlrev_b32_e32 v204, 16, v215
	v_and_b32_e32 v205, 0xffff0000, v215
	v_pk_mul_f32 v[34:35], v[34:35], v[204:205]
	v_cvt_pk_bf16_f32 v36, v36, v37
	v_cvt_pk_bf16_f32 v37, v38, v39
	v_cvt_pk_bf16_f32 v38, v32, v33
	v_cvt_pk_bf16_f32 v39, v34, v35
	global_store_dwordx4 v146, v[36:39], s[0:1] offset:256
	s_waitcnt vmcnt(15)
	v_lshlrev_b32_e32 v140, 16, v220
	v_and_b32_e32 v141, 0xffff0000, v220
	v_pk_mul_f32 v[28:29], v[28:29], v[140:141]
	v_lshlrev_b32_e32 v150, 16, v221
	v_and_b32_e32 v151, 0xffff0000, v221
	v_pk_mul_f32 v[30:31], v[30:31], v[150:151]
	v_lshlrev_b32_e32 v156, 16, v222
	v_and_b32_e32 v157, 0xffff0000, v222
	v_pk_mul_f32 v[24:25], v[24:25], v[156:157]
	v_lshlrev_b32_e32 v204, 16, v223
	v_and_b32_e32 v205, 0xffff0000, v223
	v_pk_mul_f32 v[26:27], v[26:27], v[204:205]
	v_cvt_pk_bf16_f32 v28, v28, v29
	v_cvt_pk_bf16_f32 v29, v30, v31
	v_cvt_pk_bf16_f32 v30, v24, v25
	v_cvt_pk_bf16_f32 v31, v26, v27
	global_store_dwordx4 v147, v[28:31], s[0:1]
	s_waitcnt vmcnt(15)
	v_lshlrev_b32_e32 v140, 16, v224
	v_and_b32_e32 v141, 0xffff0000, v224
	v_pk_mul_f32 v[20:21], v[20:21], v[140:141]
	v_lshlrev_b32_e32 v150, 16, v225
	v_and_b32_e32 v151, 0xffff0000, v225
	v_pk_mul_f32 v[22:23], v[22:23], v[150:151]
	v_lshlrev_b32_e32 v156, 16, v226
	v_and_b32_e32 v157, 0xffff0000, v226
	v_pk_mul_f32 v[16:17], v[16:17], v[156:157]
	v_lshlrev_b32_e32 v204, 16, v227
	v_and_b32_e32 v205, 0xffff0000, v227
	v_pk_mul_f32 v[18:19], v[18:19], v[204:205]
	v_cvt_pk_bf16_f32 v20, v20, v21
	v_cvt_pk_bf16_f32 v21, v22, v23
	v_cvt_pk_bf16_f32 v22, v16, v17
	v_cvt_pk_bf16_f32 v23, v18, v19
	global_store_dwordx4 v147, v[20:23], s[0:1] offset:256
	s_waitcnt vmcnt(15)
	v_lshlrev_b32_e32 v140, 16, v228
	v_and_b32_e32 v141, 0xffff0000, v228
	v_pk_mul_f32 v[12:13], v[12:13], v[140:141]
	v_lshlrev_b32_e32 v150, 16, v229
	v_and_b32_e32 v151, 0xffff0000, v229
	v_pk_mul_f32 v[14:15], v[14:15], v[150:151]
	v_lshlrev_b32_e32 v156, 16, v230
	v_and_b32_e32 v157, 0xffff0000, v230
	v_pk_mul_f32 v[8:9], v[8:9], v[156:157]
	v_lshlrev_b32_e32 v204, 16, v231
	v_and_b32_e32 v205, 0xffff0000, v231
	v_pk_mul_f32 v[10:11], v[10:11], v[204:205]
	v_cvt_pk_bf16_f32 v12, v12, v13
	v_cvt_pk_bf16_f32 v13, v14, v15
	v_cvt_pk_bf16_f32 v14, v8, v9
	v_cvt_pk_bf16_f32 v15, v10, v11
	global_store_dwordx4 v219, v[12:15], s[0:1]
	s_waitcnt vmcnt(15)
	v_lshlrev_b32_e32 v140, 16, v232
	v_and_b32_e32 v141, 0xffff0000, v232
	v_pk_mul_f32 v[4:5], v[4:5], v[140:141]
	v_lshlrev_b32_e32 v150, 16, v233
	v_and_b32_e32 v151, 0xffff0000, v233
	v_pk_mul_f32 v[6:7], v[6:7], v[150:151]
	v_lshlrev_b32_e32 v156, 16, v234
	v_and_b32_e32 v157, 0xffff0000, v234
	v_pk_mul_f32 v[0:1], v[0:1], v[156:157]
	v_lshlrev_b32_e32 v204, 16, v235
	v_and_b32_e32 v205, 0xffff0000, v235
	v_pk_mul_f32 v[2:3], v[2:3], v[204:205]
	v_cvt_pk_bf16_f32 v4, v4, v5
	v_cvt_pk_bf16_f32 v5, v6, v7
	v_cvt_pk_bf16_f32 v6, v0, v1
	v_cvt_pk_bf16_f32 v7, v2, v3
	global_store_dwordx4 v219, v[4:7], s[0:1] offset:256
	s_branch .Lgate_done
.Lgate_second:
	global_load_dwordx4 v[160:163], v138, s[10:11]
	global_load_dwordx4 v[192:195], v138, s[0:1]
	global_load_dwordx4 v[164:167], v138, s[10:11] offset:256
	global_load_dwordx4 v[196:199], v138, s[0:1] offset:256
	global_load_dwordx4 v[168:171], v139, s[10:11]
	global_load_dwordx4 v[200:203], v139, s[0:1]
	global_load_dwordx4 v[172:175], v139, s[10:11] offset:256
	global_load_dwordx4 v[212:215], v139, s[0:1] offset:256
	global_load_dwordx4 v[176:179], v142, s[10:11]
	global_load_dwordx4 v[220:223], v142, s[0:1]
	global_load_dwordx4 v[180:183], v142, s[10:11] offset:256
	global_load_dwordx4 v[224:227], v142, s[0:1] offset:256
	global_load_dwordx4 v[184:187], v144, s[10:11]
	global_load_dwordx4 v[228:231], v144, s[0:1]
	global_load_dwordx4 v[188:191], v144, s[10:11] offset:256
	global_load_dwordx4 v[232:235], v144, s[0:1] offset:256
	s_waitcnt vmcnt(14)
	v_lshlrev_b32_e32 v140, 16, v160
	v_and_b32_e32 v141, 0xffff0000, v160
	v_pk_mul_f32 v[124:125], v[124:125], v[140:141]
	v_lshlrev_b32_e32 v150, 16, v161
	v_and_b32_e32 v151, 0xffff0000, v161
	v_pk_mul_f32 v[126:127], v[126:127], v[150:151]
	v_lshlrev_b32_e32 v156, 16, v162
	v_and_b32_e32 v157, 0xffff0000, v162
	v_pk_mul_f32 v[120:121], v[120:121], v[156:157]
	v_lshlrev_b32_e32 v204, 16, v163
	v_and_b32_e32 v205, 0xffff0000, v163
	v_pk_mul_f32 v[122:123], v[122:123], v[204:205]
	v_lshlrev_b32_e32 v140, 16, v192
	v_and_b32_e32 v141, 0xffff0000, v192
	v_pk_add_f32 v[124:125], v[124:125], v[140:141]
	v_lshlrev_b32_e32 v150, 16, v193
	v_and_b32_e32 v151, 0xffff0000, v193
	v_pk_add_f32 v[126:127], v[126:127], v[150:151]
	v_lshlrev_b32_e32 v156, 16, v194
	v_and_b32_e32 v157, 0xffff0000, v194
	v_pk_add_f32 v[120:121], v[120:121], v[156:157]
	v_lshlrev_b32_e32 v204, 16, v195
	v_and_b32_e32 v205, 0xffff0000, v195
	v_pk_add_f32 v[122:123], v[122:123], v[204:205]
	v_cvt_pk_bf16_f32 v124, v124, v125
	v_cvt_pk_bf16_f32 v125, v126, v127
	v_cvt_pk_bf16_f32 v126, v120, v121
	v_cvt_pk_bf16_f32 v127, v122, v123
	global_store_dwordx4 v138, v[124:127], s[0:1]
	global_load_dwordx4 v[160:163], v145, s[10:11]
	global_load_dwordx4 v[192:195], v145, s[0:1]
	s_waitcnt vmcnt(15)
	v_lshlrev_b32_e32 v140, 16, v164
	v_and_b32_e32 v141, 0xffff0000, v164
	v_pk_mul_f32 v[116:117], v[116:117], v[140:141]
	v_lshlrev_b32_e32 v150, 16, v165
	v_and_b32_e32 v151, 0xffff0000, v165
	v_pk_mul_f32 v[118:119], v[118:119], v[150:151]
	v_lshlrev_b32_e32 v156, 16, v166
	v_and_b32_e32 v157, 0xffff0000, v166
	v_pk_mul_f32 v[112:113], v[112:113], v[156:157]
	v_lshlrev_b32_e32 v204, 16, v167
	v_and_b32_e32 v205, 0xffff0000, v167
	v_pk_mul_f32 v[114:115], v[114:115], v[204:205]
	v_lshlrev_b32_e32 v140, 16, v196
	v_and_b32_e32 v141, 0xffff0000, v196
	v_pk_add_f32 v[116:117], v[116:117], v[140:141]
	v_lshlrev_b32_e32 v150, 16, v197
	v_and_b32_e32 v151, 0xffff0000, v197
	v_pk_add_f32 v[118:119], v[118:119], v[150:151]
	v_lshlrev_b32_e32 v156, 16, v198
	v_and_b32_e32 v157, 0xffff0000, v198
	v_pk_add_f32 v[112:113], v[112:113], v[156:157]
	v_lshlrev_b32_e32 v204, 16, v199
	v_and_b32_e32 v205, 0xffff0000, v199
	v_pk_add_f32 v[114:115], v[114:115], v[204:205]
	v_cvt_pk_bf16_f32 v116, v116, v117
	v_cvt_pk_bf16_f32 v117, v118, v119
	v_cvt_pk_bf16_f32 v118, v112, v113
	v_cvt_pk_bf16_f32 v119, v114, v115
	global_store_dwordx4 v138, v[116:119], s[0:1] offset:256
	global_load_dwordx4 v[164:167], v145, s[10:11] offset:256
	global_load_dwordx4 v[196:199], v145, s[0:1] offset:256
	s_waitcnt vmcnt(16)
	v_lshlrev_b32_e32 v140, 16, v168
	v_and_b32_e32 v141, 0xffff0000, v168
	v_pk_mul_f32 v[108:109], v[108:109], v[140:141]
	v_lshlrev_b32_e32 v150, 16, v169
	v_and_b32_e32 v151, 0xffff0000, v169
	v_pk_mul_f32 v[110:111], v[110:111], v[150:151]
	v_lshlrev_b32_e32 v156, 16, v170
	v_and_b32_e32 v157, 0xffff0000, v170
	v_pk_mul_f32 v[104:105], v[104:105], v[156:157]
	v_lshlrev_b32_e32 v204, 16, v171
	v_and_b32_e32 v205, 0xffff0000, v171
	v_pk_mul_f32 v[106:107], v[106:107], v[204:205]
	v_lshlrev_b32_e32 v140, 16, v200
	v_and_b32_e32 v141, 0xffff0000, v200
	v_pk_add_f32 v[108:109], v[108:109], v[140:141]
	v_lshlrev_b32_e32 v150, 16, v201
	v_and_b32_e32 v151, 0xffff0000, v201
	v_pk_add_f32 v[110:111], v[110:111], v[150:151]
	v_lshlrev_b32_e32 v156, 16, v202
	v_and_b32_e32 v157, 0xffff0000, v202
	v_pk_add_f32 v[104:105], v[104:105], v[156:157]
	v_lshlrev_b32_e32 v204, 16, v203
	v_and_b32_e32 v205, 0xffff0000, v203
	v_pk_add_f32 v[106:107], v[106:107], v[204:205]
	v_cvt_pk_bf16_f32 v108, v108, v109
	v_cvt_pk_bf16_f32 v109, v110, v111
	v_cvt_pk_bf16_f32 v110, v104, v105
	v_cvt_pk_bf16_f32 v111, v106, v107
	global_store_dwordx4 v139, v[108:111], s[0:1]
	global_load_dwordx4 v[168:171], v146, s[10:11]
	global_load_dwordx4 v[200:203], v146, s[0:1]
	s_waitcnt vmcnt(17)
	v_lshlrev_b32_e32 v140, 16, v172
	v_and_b32_e32 v141, 0xffff0000, v172
	v_pk_mul_f32 v[100:101], v[100:101], v[140:141]
	v_lshlrev_b32_e32 v150, 16, v173
	v_and_b32_e32 v151, 0xffff0000, v173
	v_pk_mul_f32 v[102:103], v[102:103], v[150:151]
	v_lshlrev_b32_e32 v156, 16, v174
	v_and_b32_e32 v157, 0xffff0000, v174
	v_pk_mul_f32 v[96:97], v[96:97], v[156:157]
	v_lshlrev_b32_e32 v204, 16, v175
	v_and_b32_e32 v205, 0xffff0000, v175
	v_pk_mul_f32 v[98:99], v[98:99], v[204:205]
	v_lshlrev_b32_e32 v140, 16, v212
	v_and_b32_e32 v141, 0xffff0000, v212
	v_pk_add_f32 v[100:101], v[100:101], v[140:141]
	v_lshlrev_b32_e32 v150, 16, v213
	v_and_b32_e32 v151, 0xffff0000, v213
	v_pk_add_f32 v[102:103], v[102:103], v[150:151]
	v_lshlrev_b32_e32 v156, 16, v214
	v_and_b32_e32 v157, 0xffff0000, v214
	v_pk_add_f32 v[96:97], v[96:97], v[156:157]
	v_lshlrev_b32_e32 v204, 16, v215
	v_and_b32_e32 v205, 0xffff0000, v215
	v_pk_add_f32 v[98:99], v[98:99], v[204:205]
	v_cvt_pk_bf16_f32 v100, v100, v101
	v_cvt_pk_bf16_f32 v101, v102, v103
	v_cvt_pk_bf16_f32 v102, v96, v97
	v_cvt_pk_bf16_f32 v103, v98, v99
	global_store_dwordx4 v139, v[100:103], s[0:1] offset:256
	global_load_dwordx4 v[172:175], v146, s[10:11] offset:256
	global_load_dwordx4 v[212:215], v146, s[0:1] offset:256
	s_waitcnt vmcnt(18)
	v_lshlrev_b32_e32 v140, 16, v176
	v_and_b32_e32 v141, 0xffff0000, v176
	v_pk_mul_f32 v[92:93], v[92:93], v[140:141]
	v_lshlrev_b32_e32 v150, 16, v177
	v_and_b32_e32 v151, 0xffff0000, v177
	v_pk_mul_f32 v[94:95], v[94:95], v[150:151]
	v_lshlrev_b32_e32 v156, 16, v178
	v_and_b32_e32 v157, 0xffff0000, v178
	v_pk_mul_f32 v[88:89], v[88:89], v[156:157]
	v_lshlrev_b32_e32 v204, 16, v179
	v_and_b32_e32 v205, 0xffff0000, v179
	v_pk_mul_f32 v[90:91], v[90:91], v[204:205]
	v_lshlrev_b32_e32 v140, 16, v220
	v_and_b32_e32 v141, 0xffff0000, v220
	v_pk_add_f32 v[92:93], v[92:93], v[140:141]
	v_lshlrev_b32_e32 v150, 16, v221
	v_and_b32_e32 v151, 0xffff0000, v221
	v_pk_add_f32 v[94:95], v[94:95], v[150:151]
	v_lshlrev_b32_e32 v156, 16, v222
	v_and_b32_e32 v157, 0xffff0000, v222
	v_pk_add_f32 v[88:89], v[88:89], v[156:157]
	v_lshlrev_b32_e32 v204, 16, v223
	v_and_b32_e32 v205, 0xffff0000, v223
	v_pk_add_f32 v[90:91], v[90:91], v[204:205]
	v_cvt_pk_bf16_f32 v92, v92, v93
	v_cvt_pk_bf16_f32 v93, v94, v95
	v_cvt_pk_bf16_f32 v94, v88, v89
	v_cvt_pk_bf16_f32 v95, v90, v91
	global_store_dwordx4 v142, v[92:95], s[0:1]
	global_load_dwordx4 v[176:179], v147, s[10:11]
	global_load_dwordx4 v[220:223], v147, s[0:1]
	s_waitcnt vmcnt(19)
	v_lshlrev_b32_e32 v140, 16, v180
	v_and_b32_e32 v141, 0xffff0000, v180
	v_pk_mul_f32 v[84:85], v[84:85], v[140:141]
	v_lshlrev_b32_e32 v150, 16, v181
	v_and_b32_e32 v151, 0xffff0000, v181
	v_pk_mul_f32 v[86:87], v[86:87], v[150:151]
	v_lshlrev_b32_e32 v156, 16, v182
	v_and_b32_e32 v157, 0xffff0000, v182
	v_pk_mul_f32 v[80:81], v[80:81], v[156:157]
	v_lshlrev_b32_e32 v204, 16, v183
	v_and_b32_e32 v205, 0xffff0000, v183
	v_pk_mul_f32 v[82:83], v[82:83], v[204:205]
	v_lshlrev_b32_e32 v140, 16, v224
	v_and_b32_e32 v141, 0xffff0000, v224
	v_pk_add_f32 v[84:85], v[84:85], v[140:141]
	v_lshlrev_b32_e32 v150, 16, v225
	v_and_b32_e32 v151, 0xffff0000, v225
	v_pk_add_f32 v[86:87], v[86:87], v[150:151]
	v_lshlrev_b32_e32 v156, 16, v226
	v_and_b32_e32 v157, 0xffff0000, v226
	v_pk_add_f32 v[80:81], v[80:81], v[156:157]
	v_lshlrev_b32_e32 v204, 16, v227
	v_and_b32_e32 v205, 0xffff0000, v227
	v_pk_add_f32 v[82:83], v[82:83], v[204:205]
	v_cvt_pk_bf16_f32 v84, v84, v85
	v_cvt_pk_bf16_f32 v85, v86, v87
	v_cvt_pk_bf16_f32 v86, v80, v81
	v_cvt_pk_bf16_f32 v87, v82, v83
	global_store_dwordx4 v142, v[84:87], s[0:1] offset:256
	global_load_dwordx4 v[180:183], v147, s[10:11] offset:256
	global_load_dwordx4 v[224:227], v147, s[0:1] offset:256
	s_waitcnt vmcnt(20)
	v_lshlrev_b32_e32 v140, 16, v184
	v_and_b32_e32 v141, 0xffff0000, v184
	v_pk_mul_f32 v[76:77], v[76:77], v[140:141]
	v_lshlrev_b32_e32 v150, 16, v185
	v_and_b32_e32 v151, 0xffff0000, v185
	v_pk_mul_f32 v[78:79], v[78:79], v[150:151]
	v_lshlrev_b32_e32 v156, 16, v186
	v_and_b32_e32 v157, 0xffff0000, v186
	v_pk_mul_f32 v[72:73], v[72:73], v[156:157]
	v_lshlrev_b32_e32 v204, 16, v187
	v_and_b32_e32 v205, 0xffff0000, v187
	v_pk_mul_f32 v[74:75], v[74:75], v[204:205]
	v_lshlrev_b32_e32 v140, 16, v228
	v_and_b32_e32 v141, 0xffff0000, v228
	v_pk_add_f32 v[76:77], v[76:77], v[140:141]
	v_lshlrev_b32_e32 v150, 16, v229
	v_and_b32_e32 v151, 0xffff0000, v229
	v_pk_add_f32 v[78:79], v[78:79], v[150:151]
	v_lshlrev_b32_e32 v156, 16, v230
	v_and_b32_e32 v157, 0xffff0000, v230
	v_pk_add_f32 v[72:73], v[72:73], v[156:157]
	v_lshlrev_b32_e32 v204, 16, v231
	v_and_b32_e32 v205, 0xffff0000, v231
	v_pk_add_f32 v[74:75], v[74:75], v[204:205]
	v_cvt_pk_bf16_f32 v76, v76, v77
	v_cvt_pk_bf16_f32 v77, v78, v79
	v_cvt_pk_bf16_f32 v78, v72, v73
	v_cvt_pk_bf16_f32 v79, v74, v75
	global_store_dwordx4 v144, v[76:79], s[0:1]
	global_load_dwordx4 v[184:187], v219, s[10:11]
	global_load_dwordx4 v[228:231], v219, s[0:1]
	s_waitcnt vmcnt(21)
	v_lshlrev_b32_e32 v140, 16, v188
	v_and_b32_e32 v141, 0xffff0000, v188
	v_pk_mul_f32 v[68:69], v[68:69], v[140:141]
	v_lshlrev_b32_e32 v150, 16, v189
	v_and_b32_e32 v151, 0xffff0000, v189
	v_pk_mul_f32 v[70:71], v[70:71], v[150:151]
	v_lshlrev_b32_e32 v156, 16, v190
	v_and_b32_e32 v157, 0xffff0000, v190
	v_pk_mul_f32 v[64:65], v[64:65], v[156:157]
	v_lshlrev_b32_e32 v204, 16, v191
	v_and_b32_e32 v205, 0xffff0000, v191
	v_pk_mul_f32 v[66:67], v[66:67], v[204:205]
	v_lshlrev_b32_e32 v140, 16, v232
	v_and_b32_e32 v141, 0xffff0000, v232
	v_pk_add_f32 v[68:69], v[68:69], v[140:141]
	v_lshlrev_b32_e32 v150, 16, v233
	v_and_b32_e32 v151, 0xffff0000, v233
	v_pk_add_f32 v[70:71], v[70:71], v[150:151]
	v_lshlrev_b32_e32 v156, 16, v234
	v_and_b32_e32 v157, 0xffff0000, v234
	v_pk_add_f32 v[64:65], v[64:65], v[156:157]
	v_lshlrev_b32_e32 v204, 16, v235
	v_and_b32_e32 v205, 0xffff0000, v235
	v_pk_add_f32 v[66:67], v[66:67], v[204:205]
	v_cvt_pk_bf16_f32 v68, v68, v69
	v_cvt_pk_bf16_f32 v69, v70, v71
	v_cvt_pk_bf16_f32 v70, v64, v65
	v_cvt_pk_bf16_f32 v71, v66, v67
	global_store_dwordx4 v144, v[68:71], s[0:1] offset:256
	global_load_dwordx4 v[188:191], v219, s[10:11] offset:256
	global_load_dwordx4 v[232:235], v219, s[0:1] offset:256
	s_waitcnt vmcnt(21)
	v_lshlrev_b32_e32 v140, 16, v160
	v_and_b32_e32 v141, 0xffff0000, v160
	v_pk_mul_f32 v[60:61], v[60:61], v[140:141]
	v_lshlrev_b32_e32 v150, 16, v161
	v_and_b32_e32 v151, 0xffff0000, v161
	v_pk_mul_f32 v[62:63], v[62:63], v[150:151]
	v_lshlrev_b32_e32 v156, 16, v162
	v_and_b32_e32 v157, 0xffff0000, v162
	v_pk_mul_f32 v[56:57], v[56:57], v[156:157]
	v_lshlrev_b32_e32 v204, 16, v163
	v_and_b32_e32 v205, 0xffff0000, v163
	v_pk_mul_f32 v[58:59], v[58:59], v[204:205]
	v_lshlrev_b32_e32 v140, 16, v192
	v_and_b32_e32 v141, 0xffff0000, v192
	v_pk_add_f32 v[60:61], v[60:61], v[140:141]
	v_lshlrev_b32_e32 v150, 16, v193
	v_and_b32_e32 v151, 0xffff0000, v193
	v_pk_add_f32 v[62:63], v[62:63], v[150:151]
	v_lshlrev_b32_e32 v156, 16, v194
	v_and_b32_e32 v157, 0xffff0000, v194
	v_pk_add_f32 v[56:57], v[56:57], v[156:157]
	v_lshlrev_b32_e32 v204, 16, v195
	v_and_b32_e32 v205, 0xffff0000, v195
	v_pk_add_f32 v[58:59], v[58:59], v[204:205]
	v_cvt_pk_bf16_f32 v60, v60, v61
	v_cvt_pk_bf16_f32 v61, v62, v63
	v_cvt_pk_bf16_f32 v62, v56, v57
	v_cvt_pk_bf16_f32 v63, v58, v59
	global_store_dwordx4 v145, v[60:63], s[0:1]
	s_waitcnt vmcnt(19)
	v_lshlrev_b32_e32 v140, 16, v164
	v_and_b32_e32 v141, 0xffff0000, v164
	v_pk_mul_f32 v[52:53], v[52:53], v[140:141]
	v_lshlrev_b32_e32 v150, 16, v165
	v_and_b32_e32 v151, 0xffff0000, v165
	v_pk_mul_f32 v[54:55], v[54:55], v[150:151]
	v_lshlrev_b32_e32 v156, 16, v166
	v_and_b32_e32 v157, 0xffff0000, v166
	v_pk_mul_f32 v[48:49], v[48:49], v[156:157]
	v_lshlrev_b32_e32 v204, 16, v167
	v_and_b32_e32 v205, 0xffff0000, v167
	v_pk_mul_f32 v[50:51], v[50:51], v[204:205]
	v_lshlrev_b32_e32 v140, 16, v196
	v_and_b32_e32 v141, 0xffff0000, v196
	v_pk_add_f32 v[52:53], v[52:53], v[140:141]
	v_lshlrev_b32_e32 v150, 16, v197
	v_and_b32_e32 v151, 0xffff0000, v197
	v_pk_add_f32 v[54:55], v[54:55], v[150:151]
	v_lshlrev_b32_e32 v156, 16, v198
	v_and_b32_e32 v157, 0xffff0000, v198
	v_pk_add_f32 v[48:49], v[48:49], v[156:157]
	v_lshlrev_b32_e32 v204, 16, v199
	v_and_b32_e32 v205, 0xffff0000, v199
	v_pk_add_f32 v[50:51], v[50:51], v[204:205]
	v_cvt_pk_bf16_f32 v52, v52, v53
	v_cvt_pk_bf16_f32 v53, v54, v55
	v_cvt_pk_bf16_f32 v54, v48, v49
	v_cvt_pk_bf16_f32 v55, v50, v51
	global_store_dwordx4 v145, v[52:55], s[0:1] offset:256
	s_waitcnt vmcnt(17)
	v_lshlrev_b32_e32 v140, 16, v168
	v_and_b32_e32 v141, 0xffff0000, v168
	v_pk_mul_f32 v[44:45], v[44:45], v[140:141]
	v_lshlrev_b32_e32 v150, 16, v169
	v_and_b32_e32 v151, 0xffff0000, v169
	v_pk_mul_f32 v[46:47], v[46:47], v[150:151]
	v_lshlrev_b32_e32 v156, 16, v170
	v_and_b32_e32 v157, 0xffff0000, v170
	v_pk_mul_f32 v[40:41], v[40:41], v[156:157]
	v_lshlrev_b32_e32 v204, 16, v171
	v_and_b32_e32 v205, 0xffff0000, v171
	v_pk_mul_f32 v[42:43], v[42:43], v[204:205]
	v_lshlrev_b32_e32 v140, 16, v200
	v_and_b32_e32 v141, 0xffff0000, v200
	v_pk_add_f32 v[44:45], v[44:45], v[140:141]
	v_lshlrev_b32_e32 v150, 16, v201
	v_and_b32_e32 v151, 0xffff0000, v201
	v_pk_add_f32 v[46:47], v[46:47], v[150:151]
	v_lshlrev_b32_e32 v156, 16, v202
	v_and_b32_e32 v157, 0xffff0000, v202
	v_pk_add_f32 v[40:41], v[40:41], v[156:157]
	v_lshlrev_b32_e32 v204, 16, v203
	v_and_b32_e32 v205, 0xffff0000, v203
	v_pk_add_f32 v[42:43], v[42:43], v[204:205]
	v_cvt_pk_bf16_f32 v44, v44, v45
	v_cvt_pk_bf16_f32 v45, v46, v47
	v_cvt_pk_bf16_f32 v46, v40, v41
	v_cvt_pk_bf16_f32 v47, v42, v43
	global_store_dwordx4 v146, v[44:47], s[0:1]
	s_waitcnt vmcnt(15)
	v_lshlrev_b32_e32 v140, 16, v172
	v_and_b32_e32 v141, 0xffff0000, v172
	v_pk_mul_f32 v[36:37], v[36:37], v[140:141]
	v_lshlrev_b32_e32 v150, 16, v173
	v_and_b32_e32 v151, 0xffff0000, v173
	v_pk_mul_f32 v[38:39], v[38:39], v[150:151]
	v_lshlrev_b32_e32 v156, 16, v174
	v_and_b32_e32 v157, 0xffff0000, v174
	v_pk_mul_f32 v[32:33], v[32:33], v[156:157]
	v_lshlrev_b32_e32 v204, 16, v175
	v_and_b32_e32 v205, 0xffff0000, v175
	v_pk_mul_f32 v[34:35], v[34:35], v[204:205]
	v_lshlrev_b32_e32 v140, 16, v212
	v_and_b32_e32 v141, 0xffff0000, v212
	v_pk_add_f32 v[36:37], v[36:37], v[140:141]
	v_lshlrev_b32_e32 v150, 16, v213
	v_and_b32_e32 v151, 0xffff0000, v213
	v_pk_add_f32 v[38:39], v[38:39], v[150:151]
	v_lshlrev_b32_e32 v156, 16, v214
	v_and_b32_e32 v157, 0xffff0000, v214
	v_pk_add_f32 v[32:33], v[32:33], v[156:157]
	v_lshlrev_b32_e32 v204, 16, v215
	v_and_b32_e32 v205, 0xffff0000, v215
	v_pk_add_f32 v[34:35], v[34:35], v[204:205]
	v_cvt_pk_bf16_f32 v36, v36, v37
	v_cvt_pk_bf16_f32 v37, v38, v39
	v_cvt_pk_bf16_f32 v38, v32, v33
	v_cvt_pk_bf16_f32 v39, v34, v35
	global_store_dwordx4 v146, v[36:39], s[0:1] offset:256
	s_waitcnt vmcnt(13)
	v_lshlrev_b32_e32 v140, 16, v176
	v_and_b32_e32 v141, 0xffff0000, v176
	v_pk_mul_f32 v[28:29], v[28:29], v[140:141]
	v_lshlrev_b32_e32 v150, 16, v177
	v_and_b32_e32 v151, 0xffff0000, v177
	v_pk_mul_f32 v[30:31], v[30:31], v[150:151]
	v_lshlrev_b32_e32 v156, 16, v178
	v_and_b32_e32 v157, 0xffff0000, v178
	v_pk_mul_f32 v[24:25], v[24:25], v[156:157]
	v_lshlrev_b32_e32 v204, 16, v179
	v_and_b32_e32 v205, 0xffff0000, v179
	v_pk_mul_f32 v[26:27], v[26:27], v[204:205]
	v_lshlrev_b32_e32 v140, 16, v220
	v_and_b32_e32 v141, 0xffff0000, v220
	v_pk_add_f32 v[28:29], v[28:29], v[140:141]
	v_lshlrev_b32_e32 v150, 16, v221
	v_and_b32_e32 v151, 0xffff0000, v221
	v_pk_add_f32 v[30:31], v[30:31], v[150:151]
	v_lshlrev_b32_e32 v156, 16, v222
	v_and_b32_e32 v157, 0xffff0000, v222
	v_pk_add_f32 v[24:25], v[24:25], v[156:157]
	v_lshlrev_b32_e32 v204, 16, v223
	v_and_b32_e32 v205, 0xffff0000, v223
	v_pk_add_f32 v[26:27], v[26:27], v[204:205]
	v_cvt_pk_bf16_f32 v28, v28, v29
	v_cvt_pk_bf16_f32 v29, v30, v31
	v_cvt_pk_bf16_f32 v30, v24, v25
	v_cvt_pk_bf16_f32 v31, v26, v27
	global_store_dwordx4 v147, v[28:31], s[0:1]
	s_waitcnt vmcnt(11)
	v_lshlrev_b32_e32 v140, 16, v180
	v_and_b32_e32 v141, 0xffff0000, v180
	v_pk_mul_f32 v[20:21], v[20:21], v[140:141]
	v_lshlrev_b32_e32 v150, 16, v181
	v_and_b32_e32 v151, 0xffff0000, v181
	v_pk_mul_f32 v[22:23], v[22:23], v[150:151]
	v_lshlrev_b32_e32 v156, 16, v182
	v_and_b32_e32 v157, 0xffff0000, v182
	v_pk_mul_f32 v[16:17], v[16:17], v[156:157]
	v_lshlrev_b32_e32 v204, 16, v183
	v_and_b32_e32 v205, 0xffff0000, v183
	v_pk_mul_f32 v[18:19], v[18:19], v[204:205]
	v_lshlrev_b32_e32 v140, 16, v224
	v_and_b32_e32 v141, 0xffff0000, v224
	v_pk_add_f32 v[20:21], v[20:21], v[140:141]
	v_lshlrev_b32_e32 v150, 16, v225
	v_and_b32_e32 v151, 0xffff0000, v225
	v_pk_add_f32 v[22:23], v[22:23], v[150:151]
	v_lshlrev_b32_e32 v156, 16, v226
	v_and_b32_e32 v157, 0xffff0000, v226
	v_pk_add_f32 v[16:17], v[16:17], v[156:157]
	v_lshlrev_b32_e32 v204, 16, v227
	v_and_b32_e32 v205, 0xffff0000, v227
	v_pk_add_f32 v[18:19], v[18:19], v[204:205]
	v_cvt_pk_bf16_f32 v20, v20, v21
	v_cvt_pk_bf16_f32 v21, v22, v23
	v_cvt_pk_bf16_f32 v22, v16, v17
	v_cvt_pk_bf16_f32 v23, v18, v19
	global_store_dwordx4 v147, v[20:23], s[0:1] offset:256
	s_waitcnt vmcnt(9)
	v_lshlrev_b32_e32 v140, 16, v184
	v_and_b32_e32 v141, 0xffff0000, v184
	v_pk_mul_f32 v[12:13], v[12:13], v[140:141]
	v_lshlrev_b32_e32 v150, 16, v185
	v_and_b32_e32 v151, 0xffff0000, v185
	v_pk_mul_f32 v[14:15], v[14:15], v[150:151]
	v_lshlrev_b32_e32 v156, 16, v186
	v_and_b32_e32 v157, 0xffff0000, v186
	v_pk_mul_f32 v[8:9], v[8:9], v[156:157]
	v_lshlrev_b32_e32 v204, 16, v187
	v_and_b32_e32 v205, 0xffff0000, v187
	v_pk_mul_f32 v[10:11], v[10:11], v[204:205]
	v_lshlrev_b32_e32 v140, 16, v228
	v_and_b32_e32 v141, 0xffff0000, v228
	v_pk_add_f32 v[12:13], v[12:13], v[140:141]
	v_lshlrev_b32_e32 v150, 16, v229
	v_and_b32_e32 v151, 0xffff0000, v229
	v_pk_add_f32 v[14:15], v[14:15], v[150:151]
	v_lshlrev_b32_e32 v156, 16, v230
	v_and_b32_e32 v157, 0xffff0000, v230
	v_pk_add_f32 v[8:9], v[8:9], v[156:157]
	v_lshlrev_b32_e32 v204, 16, v231
	v_and_b32_e32 v205, 0xffff0000, v231
	v_pk_add_f32 v[10:11], v[10:11], v[204:205]
	v_cvt_pk_bf16_f32 v12, v12, v13
	v_cvt_pk_bf16_f32 v13, v14, v15
	v_cvt_pk_bf16_f32 v14, v8, v9
	v_cvt_pk_bf16_f32 v15, v10, v11
	global_store_dwordx4 v219, v[12:15], s[0:1]
	s_waitcnt vmcnt(7)
	v_lshlrev_b32_e32 v140, 16, v188
	v_and_b32_e32 v141, 0xffff0000, v188
	v_pk_mul_f32 v[4:5], v[4:5], v[140:141]
	v_lshlrev_b32_e32 v150, 16, v189
	v_and_b32_e32 v151, 0xffff0000, v189
	v_pk_mul_f32 v[6:7], v[6:7], v[150:151]
	v_lshlrev_b32_e32 v156, 16, v190
	v_and_b32_e32 v157, 0xffff0000, v190
	v_pk_mul_f32 v[0:1], v[0:1], v[156:157]
	v_lshlrev_b32_e32 v204, 16, v191
	v_and_b32_e32 v205, 0xffff0000, v191
	v_pk_mul_f32 v[2:3], v[2:3], v[204:205]
	v_lshlrev_b32_e32 v140, 16, v232
	v_and_b32_e32 v141, 0xffff0000, v232
	v_pk_add_f32 v[4:5], v[4:5], v[140:141]
	v_lshlrev_b32_e32 v150, 16, v233
	v_and_b32_e32 v151, 0xffff0000, v233
	v_pk_add_f32 v[6:7], v[6:7], v[150:151]
	v_lshlrev_b32_e32 v156, 16, v234
	v_and_b32_e32 v157, 0xffff0000, v234
	v_pk_add_f32 v[0:1], v[0:1], v[156:157]
	v_lshlrev_b32_e32 v204, 16, v235
	v_and_b32_e32 v205, 0xffff0000, v235
	v_pk_add_f32 v[2:3], v[2:3], v[204:205]
	v_cvt_pk_bf16_f32 v4, v4, v5
	v_cvt_pk_bf16_f32 v5, v6, v7
	v_cvt_pk_bf16_f32 v6, v0, v1
	v_cvt_pk_bf16_f32 v7, v2, v3
	global_store_dwordx4 v219, v[4:7], s[0:1] offset:256
.Lgate_done:
	s_andn2_b64 vcc, exec, s[6:7]
	s_mov_b64 s[6:7], -1
	s_cbranch_vccnz .LBB0_1327
	s_andn2_b64 vcc, exec, s[4:5]
	s_cbranch_vccnz .LBB0_1326
	s_barrier
	s_branch .LBB0_1326
